# c13 + attention queue hands out one (seq,head) unit at a time (sequence-major q-tile order: smaller K/V working set per XCD L2)
# speedup vs baseline: 1.0027x; 1.0027x over previous
.LBB0_815:
	s_waitcnt lgkmcnt(0)
	s_barrier
	ds_read_b32 v0, v102
	s_movk_i32 s0, 0x8f
	s_waitcnt lgkmcnt(0)
	v_cmp_lt_i32_e32 vcc, s0, v0
	v_readfirstlane_b32 s4, v0
	s_mov_b64 s[0:1], -1
	s_cbranch_vccnz .LBB0_808
	s_and_b32 s0, s4, 63
	s_lshl_b32 s0, s0, 4
	s_lshr_b32 s1, s4, 6
	s_lshl_b32 s1, s1, 3
	s_or_b32 s0, s0, s1
	s_or_b32 s0, s0, s49
	s_add_i32 s1, s50, s4
	s_cmpk_lt_i32 s4, 0x80
	s_cselect_b32 s5, s0, s1
	s_cmpk_gt_i32 s5, 0x3ff
	s_mov_b64 s[0:1], -1
	v_mbcnt_lo_u32_b32 v0, -1, 0
	v_mbcnt_hi_u32_b32 v0, -1, v0
	s_cbranch_scc0 .LBB0_818
	s_add_i32 s0, s5, 0xfffffc00
	s_lshr_b32 s4, s0, 3
	s_mov_b64 s[0:1], 0
